# P7 router: fuse the two rows of an iteration into one pass (each LDS weight read feeds both rows, shuffle/softmax chains interleaved)
# speedup vs baseline: 1.0065x; 1.0065x over previous
; DI void phase7(const Params& p, char* smem) {
;     ...
;   auto router = [&](const float4 (&v)[4], int R) {
;     asm volatile("" ::: "memory");
;     float a[16];
; #pragma unroll
;     for (int e = 0; e < 16; ++e) {
;       float s = 0.f;
; #pragma unroll
;       for (int i = 0; i < 4; ++i) { const float4 wv = *(const float4*)(wr + e * DM + lane * 4 + 256 * i); s += v[i].x * wv.x + v[i].y * wv.y + v[i].z * wv.z + v[i].w * wv.w; }
;       a[e] = s;
;       if ((e & 3) == 3) __builtin_amdgcn_sched_barrier(0);
;     }
.LBB0_963:
	s_or_b64 exec, exec, s[16:17]
	ds_read_b128 v[0:3], v8
	ds_read_b128 v[64:67], v8 offset:1024
	ds_read_b128 v[68:71], v8 offset:2048
	s_waitcnt lgkmcnt(2)
	v_mul_f32_e32 v111, v47, v1
	v_mul_f32_e32 v1, v49, v1
	s_waitcnt lgkmcnt(1)
	v_mul_f32_e32 v116, v45, v65
	v_mul_f32_e32 v6, v55, v65
	v_fmac_f32_e32 v111, v46, v0
	v_fmac_f32_e32 v1, v48, v0
	v_fmac_f32_e32 v116, v44, v64
	v_fmac_f32_e32 v6, v54, v64
	v_fmac_f32_e32 v111, v42, v2
	v_fmac_f32_e32 v1, v50, v2
	v_fmac_f32_e32 v111, v43, v3
	v_fmac_f32_e32 v1, v51, v3
	v_fmac_f32_e32 v116, v38, v66
	v_fmac_f32_e32 v6, v52, v66
	v_add_f32_e32 v110, 0, v111
	v_add_f32_e32 v0, 0, v1
	v_fmac_f32_e32 v116, v39, v67
	v_fmac_f32_e32 v6, v53, v67
	v_add_f32_e32 v116, v110, v116
	v_add_f32_e32 v6, v0, v6
	ds_read_b128 v[0:3], v8 offset:3072
	ds_read_b128 v[64:67], v8 offset:4096
	s_waitcnt lgkmcnt(2)
	v_mul_f32_e32 v119, v41, v69
	v_mul_f32_e32 v9, v59, v69
	v_fmac_f32_e32 v119, v40, v68
	v_fmac_f32_e32 v9, v58, v68
	v_fmac_f32_e32 v119, v34, v70
	v_fmac_f32_e32 v9, v56, v70
	s_waitcnt lgkmcnt(1)
	v_mul_f32_e32 v111, v37, v1
	v_mul_f32_e32 v1, v63, v1
	v_fmac_f32_e32 v111, v36, v0
	v_fmac_f32_e32 v1, v62, v0
	v_fmac_f32_e32 v119, v35, v71
	v_fmac_f32_e32 v9, v57, v71
	v_fmac_f32_e32 v111, v32, v2
	v_fmac_f32_e32 v1, v60, v2
	v_add_f32_e32 v116, v116, v119
	v_add_f32_e32 v6, v6, v9
	v_fmac_f32_e32 v111, v33, v3
	v_fmac_f32_e32 v1, v61, v3
	ds_read_b128 v[68:71], v8 offset:5120
	v_add_f32_e32 v110, v116, v111
	v_add_f32_e32 v0, v6, v1
	s_waitcnt lgkmcnt(1)
	v_mul_f32_e32 v111, v47, v65
	v_mul_f32_e32 v1, v49, v65
	v_fmac_f32_e32 v111, v46, v64
	v_fmac_f32_e32 v1, v48, v64
	v_fmac_f32_e32 v111, v42, v66
	v_fmac_f32_e32 v1, v50, v66
	v_fmac_f32_e32 v111, v43, v67
	v_fmac_f32_e32 v1, v51, v67
	ds_read_b128 v[64:67], v8 offset:6144
	s_waitcnt lgkmcnt(1)
	v_mul_f32_e32 v112, v45, v69
	v_mul_f32_e32 v2, v55, v69
	v_fmac_f32_e32 v112, v44, v68
	v_fmac_f32_e32 v2, v54, v68
	v_fmac_f32_e32 v112, v38, v70
	v_fmac_f32_e32 v2, v52, v70
	v_add_f32_e32 v111, 0, v111
	v_add_f32_e32 v1, 0, v1
	v_fmac_f32_e32 v112, v39, v71
	v_fmac_f32_e32 v2, v53, v71
	ds_read_b128 v[68:71], v8 offset:7168
	v_add_f32_e32 v111, v111, v112
	v_add_f32_e32 v1, v1, v2
	s_waitcnt lgkmcnt(1)
	v_mul_f32_e32 v112, v41, v65
	v_mul_f32_e32 v2, v59, v65
	v_fmac_f32_e32 v112, v40, v64
	v_fmac_f32_e32 v2, v58, v64
	v_fmac_f32_e32 v112, v34, v66
	v_fmac_f32_e32 v2, v56, v66
	v_fmac_f32_e32 v112, v35, v67
	v_fmac_f32_e32 v2, v57, v67
	ds_read_b128 v[64:67], v8 offset:9216
	ds_read_b128 v[72:75], v8 offset:8192
	v_add_f32_e32 v111, v111, v112
	v_add_f32_e32 v1, v1, v2
	s_waitcnt lgkmcnt(2)
	v_mul_f32_e32 v112, v37, v69
	v_mul_f32_e32 v2, v63, v69
	v_fmac_f32_e32 v112, v36, v68
	v_fmac_f32_e32 v2, v62, v68
	v_fmac_f32_e32 v112, v32, v70
	v_fmac_f32_e32 v2, v60, v70
	v_fmac_f32_e32 v112, v33, v71
	v_fmac_f32_e32 v2, v61, v71
	v_add_f32_e32 v111, v111, v112
	v_add_f32_e32 v1, v1, v2
	ds_read_b128 v[68:71], v8 offset:11264
	ds_read_b128 v[78:81], v8 offset:10240
	s_waitcnt lgkmcnt(2)
	v_mul_f32_e32 v112, v46, v72
	v_mul_f32_e32 v2, v48, v72
	v_fmac_f32_e32 v112, v47, v73
	v_fmac_f32_e32 v2, v49, v73
	v_mul_f32_e32 v113, v44, v64
	v_mul_f32_e32 v3, v54, v64
	v_fmac_f32_e32 v112, v42, v74
	v_fmac_f32_e32 v2, v50, v74
	v_fmac_f32_e32 v113, v45, v65
	v_fmac_f32_e32 v3, v55, v65
	v_fmac_f32_e32 v112, v43, v75
	v_fmac_f32_e32 v2, v51, v75
	v_fmac_f32_e32 v113, v38, v66
	v_fmac_f32_e32 v3, v52, v66
	v_add_f32_e32 v112, 0, v112
	v_add_f32_e32 v2, 0, v2
	v_fmac_f32_e32 v113, v39, v67
	v_fmac_f32_e32 v3, v53, v67
	v_add_f32_e32 v112, v113, v112
	v_add_f32_e32 v2, v3, v2
	s_waitcnt lgkmcnt(0)
	v_mul_f32_e32 v113, v40, v78
	v_mul_f32_e32 v3, v58, v78
	v_fmac_f32_e32 v113, v41, v79
	v_fmac_f32_e32 v3, v59, v79
	v_fmac_f32_e32 v113, v34, v80
	v_fmac_f32_e32 v3, v56, v80
	v_fmac_f32_e32 v113, v35, v81
	v_fmac_f32_e32 v3, v57, v81
	ds_read_b128 v[64:67], v8 offset:13312
	ds_read_b128 v[72:75], v8 offset:12288
	v_add_f32_e32 v112, v113, v112
	v_add_f32_e32 v2, v3, v2
	v_mul_f32_e32 v113, v36, v68
	v_mul_f32_e32 v3, v62, v68
	v_fmac_f32_e32 v113, v37, v69
	v_fmac_f32_e32 v3, v63, v69
	v_fmac_f32_e32 v113, v32, v70
	v_fmac_f32_e32 v3, v60, v70
	v_fmac_f32_e32 v113, v33, v71
	v_fmac_f32_e32 v3, v61, v71
	v_add_f32_e32 v112, v113, v112
	v_add_f32_e32 v2, v3, v2
	ds_read_b128 v[68:71], v8 offset:15360
	ds_read_b128 v[78:81], v8 offset:14336
	s_waitcnt lgkmcnt(2)
	v_mul_f32_e32 v113, v46, v72
	v_mul_f32_e32 v3, v48, v72
	v_fmac_f32_e32 v113, v47, v73
	v_fmac_f32_e32 v3, v49, v73
	v_mul_f32_e32 v116, v44, v64
	v_mul_f32_e32 v6, v54, v64
	v_fmac_f32_e32 v113, v42, v74
	v_fmac_f32_e32 v3, v50, v74
	v_fmac_f32_e32 v116, v45, v65
	v_fmac_f32_e32 v6, v55, v65
	v_fmac_f32_e32 v113, v43, v75
	v_fmac_f32_e32 v3, v51, v75
	v_fmac_f32_e32 v116, v38, v66
	v_fmac_f32_e32 v6, v52, v66
	v_add_f32_e32 v113, 0, v113
	v_add_f32_e32 v3, 0, v3
	v_fmac_f32_e32 v116, v39, v67
	v_fmac_f32_e32 v6, v53, v67
	v_add_f32_e32 v113, v116, v113
	v_add_f32_e32 v3, v6, v3
	s_waitcnt lgkmcnt(0)
	v_mul_f32_e32 v116, v40, v78
	v_mul_f32_e32 v6, v58, v78
	v_fmac_f32_e32 v116, v41, v79
	v_fmac_f32_e32 v6, v59, v79
	v_fmac_f32_e32 v116, v34, v80
	v_fmac_f32_e32 v6, v56, v80
	v_fmac_f32_e32 v116, v35, v81
	v_fmac_f32_e32 v6, v57, v81
	v_add_f32_e32 v113, v116, v113
	v_add_f32_e32 v3, v6, v3
	v_mul_f32_e32 v116, v36, v68
	v_mul_f32_e32 v6, v62, v68
	v_fmac_f32_e32 v116, v37, v69
	v_fmac_f32_e32 v6, v63, v69
	v_fmac_f32_e32 v116, v32, v70
	v_fmac_f32_e32 v6, v60, v70
	v_fmac_f32_e32 v116, v33, v71
	v_fmac_f32_e32 v6, v61, v71
	v_add_f32_e32 v113, v116, v113
	v_add_f32_e32 v3, v6, v3
	ds_read_b128 v[64:67], v8 offset:16384
	ds_read_b128 v[68:71], v8 offset:17408
	ds_read_b128 v[72:75], v8 offset:18432
	s_waitcnt lgkmcnt(2)
; DI void phase7(const Params& p, char* smem) {
;     ...
; #pragma unroll
;     for (int e = 0; e < 16; ++e) {
;       float s = 0.f;
; #pragma unroll
;       for (int i = 0; i < 4; ++i) { const float4 wv = *(const float4*)(wr + e * DM + lane * 4 + 256 * i); s += v[i].x * wv.x + v[i].y * wv.y + v[i].z * wv.z + v[i].w * wv.w; }
;       a[e] = s;
;       if ((e & 3) == 3) __builtin_amdgcn_sched_barrier(0);
	v_mul_f32_e32 v116, v47, v65
	v_mul_f32_e32 v6, v49, v65
	s_waitcnt lgkmcnt(1)
	v_mul_f32_e32 v119, v45, v69
	v_mul_f32_e32 v9, v55, v69
	v_fmac_f32_e32 v116, v46, v64
	v_fmac_f32_e32 v6, v48, v64
	v_fmac_f32_e32 v119, v44, v68
	v_fmac_f32_e32 v9, v54, v68
	v_fmac_f32_e32 v116, v42, v66
	v_fmac_f32_e32 v6, v50, v66
	v_fmac_f32_e32 v116, v43, v67
	v_fmac_f32_e32 v6, v51, v67
	v_fmac_f32_e32 v119, v38, v70
	v_fmac_f32_e32 v9, v52, v70
	v_add_f32_e32 v116, 0, v116
	v_add_f32_e32 v6, 0, v6
	v_fmac_f32_e32 v119, v39, v71
	v_fmac_f32_e32 v9, v53, v71
	ds_read_b128 v[64:67], v8 offset:19456
	v_add_f32_e32 v116, v116, v119
	v_add_f32_e32 v6, v6, v9
	s_waitcnt lgkmcnt(1)
	v_mul_f32_e32 v119, v41, v73
	v_mul_f32_e32 v9, v59, v73
	v_fmac_f32_e32 v119, v40, v72
	v_fmac_f32_e32 v9, v58, v72
	v_fmac_f32_e32 v119, v34, v74
	v_fmac_f32_e32 v9, v56, v74
	v_fmac_f32_e32 v119, v35, v75
	v_fmac_f32_e32 v9, v57, v75
	ds_read_b128 v[68:71], v8 offset:21504
	ds_read_b128 v[72:75], v8 offset:20480
	v_add_f32_e32 v116, v116, v119
	v_add_f32_e32 v6, v6, v9
	s_waitcnt lgkmcnt(2)
	v_mul_f32_e32 v119, v37, v65
	v_mul_f32_e32 v9, v63, v65
	v_fmac_f32_e32 v119, v36, v64
	v_fmac_f32_e32 v9, v62, v64
	v_fmac_f32_e32 v119, v32, v66
	v_fmac_f32_e32 v9, v60, v66
	v_fmac_f32_e32 v119, v33, v67
	v_fmac_f32_e32 v9, v61, v67
	v_add_f32_e32 v116, v116, v119
	v_add_f32_e32 v6, v6, v9
	ds_read_b128 v[64:67], v8 offset:23552
	ds_read_b128 v[78:81], v8 offset:22528
	s_waitcnt lgkmcnt(2)
	v_mul_f32_e32 v119, v46, v72
	v_mul_f32_e32 v9, v48, v72
	v_fmac_f32_e32 v119, v47, v73
	v_fmac_f32_e32 v9, v49, v73
	v_mul_f32_e32 v178, v44, v68
	v_mul_f32_e32 v68, v54, v68
	v_fmac_f32_e32 v119, v42, v74
	v_fmac_f32_e32 v9, v50, v74
	v_fmac_f32_e32 v178, v45, v69
	v_fmac_f32_e32 v68, v55, v69
	v_fmac_f32_e32 v119, v43, v75
	v_fmac_f32_e32 v9, v51, v75
	v_fmac_f32_e32 v178, v38, v70
	v_fmac_f32_e32 v68, v52, v70
	v_add_f32_e32 v119, 0, v119
	v_add_f32_e32 v9, 0, v9
	v_fmac_f32_e32 v178, v39, v71
	v_fmac_f32_e32 v68, v53, v71
	v_add_f32_e32 v119, v178, v119
	v_add_f32_e32 v9, v68, v9
	s_waitcnt lgkmcnt(0)
	v_mul_f32_e32 v178, v40, v78
	v_mul_f32_e32 v68, v58, v78
	v_fmac_f32_e32 v178, v41, v79
	v_fmac_f32_e32 v68, v59, v79
	v_fmac_f32_e32 v178, v34, v80
	v_fmac_f32_e32 v68, v56, v80
	v_mul_f32_e32 v174, v36, v64
	v_mul_f32_e32 v64, v62, v64
	v_fmac_f32_e32 v178, v35, v81
	v_fmac_f32_e32 v68, v57, v81
	v_fmac_f32_e32 v174, v37, v65
	v_fmac_f32_e32 v64, v63, v65
	v_add_f32_e32 v119, v178, v119
	v_add_f32_e32 v9, v68, v9
	v_fmac_f32_e32 v174, v32, v66
	v_fmac_f32_e32 v64, v60, v66
	ds_read_b128 v[68:71], v8 offset:25600
	ds_read_b128 v[72:75], v8 offset:24576
	v_fmac_f32_e32 v174, v33, v67
	v_fmac_f32_e32 v64, v61, v67
	v_add_f32_e32 v119, v174, v119
	v_add_f32_e32 v9, v64, v9
	ds_read_b128 v[64:67], v8 offset:27648
	ds_read_b128 v[78:81], v8 offset:26624
	s_waitcnt lgkmcnt(3)
	v_mul_f32_e32 v178, v44, v68
	v_mul_f32_e32 v68, v54, v68
	s_waitcnt lgkmcnt(2)
	v_mul_f32_e32 v182, v46, v72
	v_mul_f32_e32 v72, v48, v72
	v_fmac_f32_e32 v182, v47, v73
	v_fmac_f32_e32 v72, v49, v73
	v_fmac_f32_e32 v182, v42, v74
	v_fmac_f32_e32 v72, v50, v74
	v_fmac_f32_e32 v178, v45, v69
	v_fmac_f32_e32 v68, v55, v69
	s_waitcnt lgkmcnt(0)
	v_mul_f32_e32 v179, v40, v78
	v_mul_f32_e32 v69, v58, v78
	v_fmac_f32_e32 v182, v43, v75
	v_fmac_f32_e32 v72, v51, v75
	v_fmac_f32_e32 v178, v38, v70
	v_fmac_f32_e32 v68, v52, v70
	v_fmac_f32_e32 v179, v41, v79
	v_fmac_f32_e32 v69, v59, v79
	v_add_f32_e32 v182, 0, v182
	v_add_f32_e32 v72, 0, v72
	v_fmac_f32_e32 v178, v39, v71
	v_fmac_f32_e32 v68, v53, v71
	v_fmac_f32_e32 v179, v34, v80
	v_fmac_f32_e32 v69, v56, v80
	v_mul_f32_e32 v174, v36, v64
	v_mul_f32_e32 v64, v62, v64
	v_add_f32_e32 v178, v178, v182
	v_add_f32_e32 v68, v68, v72
	v_fmac_f32_e32 v179, v35, v81
	v_fmac_f32_e32 v69, v57, v81
	v_fmac_f32_e32 v174, v37, v65
	v_fmac_f32_e32 v64, v63, v65
	v_add_f32_e32 v186, v179, v178
	v_add_f32_e32 v76, v69, v68
	v_fmac_f32_e32 v174, v32, v66
	v_fmac_f32_e32 v64, v60, v66
	ds_read_b128 v[68:71], v8 offset:29696
	ds_read_b128 v[72:75], v8 offset:28672
	v_fmac_f32_e32 v174, v33, v67
	v_fmac_f32_e32 v64, v61, v67
	v_add_f32_e32 v186, v174, v186
	v_add_f32_e32 v76, v64, v76
	ds_read_b128 v[64:67], v8 offset:31744
	ds_read_b128 v[78:81], v8 offset:30720
	s_waitcnt lgkmcnt(3)
	v_mul_f32_e32 v178, v44, v68
	v_mul_f32_e32 v68, v54, v68
	s_waitcnt lgkmcnt(2)
	v_mul_f32_e32 v182, v46, v72
	v_mul_f32_e32 v72, v48, v72
	v_fmac_f32_e32 v182, v47, v73
	v_fmac_f32_e32 v72, v49, v73
	v_fmac_f32_e32 v182, v42, v74
	v_fmac_f32_e32 v72, v50, v74
	v_fmac_f32_e32 v178, v45, v69
	v_fmac_f32_e32 v68, v55, v69
	s_waitcnt lgkmcnt(0)
	v_mul_f32_e32 v179, v40, v78
	v_mul_f32_e32 v69, v58, v78
	v_fmac_f32_e32 v182, v43, v75
	v_fmac_f32_e32 v72, v51, v75
	v_fmac_f32_e32 v178, v38, v70
	v_fmac_f32_e32 v68, v52, v70
	v_fmac_f32_e32 v179, v41, v79
	v_fmac_f32_e32 v69, v59, v79
	v_mul_f32_e32 v174, v36, v64
	v_mul_f32_e32 v64, v62, v64
	v_add_f32_e32 v182, 0, v182
	v_add_f32_e32 v72, 0, v72
	v_fmac_f32_e32 v178, v39, v71
	v_fmac_f32_e32 v68, v53, v71
	v_fmac_f32_e32 v179, v34, v80
	v_fmac_f32_e32 v69, v56, v80
	v_fmac_f32_e32 v174, v37, v65
	v_fmac_f32_e32 v64, v63, v65
	v_add_f32_e32 v178, v178, v182
	v_add_f32_e32 v68, v68, v72
	v_fmac_f32_e32 v179, v35, v81
	v_fmac_f32_e32 v69, v57, v81
	v_fmac_f32_e32 v174, v32, v66
	v_fmac_f32_e32 v64, v60, v66
	v_add_f32_e32 v178, v179, v178
	v_add_f32_e32 v68, v69, v68
	v_fmac_f32_e32 v174, v33, v67
	v_fmac_f32_e32 v64, v61, v67
	v_add_f32_e32 v192, v174, v178
	v_add_f32_e32 v82, v64, v68
	ds_read_b128 v[64:67], v8 offset:32768
	ds_read_b128 v[68:71], v8 offset:33792
	ds_read_b128 v[72:75], v8 offset:34816
	s_waitcnt lgkmcnt(2)
; DI void phase7(const Params& p, char* smem) {
;     ...
; #pragma unroll
;     for (int e = 0; e < 16; ++e) {
;       float s = 0.f;
; #pragma unroll
;       for (int i = 0; i < 4; ++i) { const float4 wv = *(const float4*)(wr + e * DM + lane * 4 + 256 * i); s += v[i].x * wv.x + v[i].y * wv.y + v[i].z * wv.z + v[i].w * wv.w; }
;       a[e] = s;
;       if ((e & 3) == 3) __builtin_amdgcn_sched_barrier(0);
	v_mul_f32_e32 v175, v47, v65
	v_mul_f32_e32 v65, v49, v65
	s_waitcnt lgkmcnt(1)
	v_mul_f32_e32 v179, v45, v69
	v_mul_f32_e32 v69, v55, v69
	v_fmac_f32_e32 v175, v46, v64
	v_fmac_f32_e32 v65, v48, v64
	v_fmac_f32_e32 v179, v44, v68
	v_fmac_f32_e32 v69, v54, v68
	v_fmac_f32_e32 v175, v42, v66
	v_fmac_f32_e32 v65, v50, v66
	v_fmac_f32_e32 v175, v43, v67
	v_fmac_f32_e32 v65, v51, v67
	v_fmac_f32_e32 v179, v38, v70
	v_fmac_f32_e32 v69, v52, v70
	v_add_f32_e32 v174, 0, v175
	v_add_f32_e32 v64, 0, v65
	v_fmac_f32_e32 v179, v39, v71
	v_fmac_f32_e32 v69, v53, v71
	v_add_f32_e32 v178, v174, v179
	v_add_f32_e32 v68, v64, v69
	ds_read_b128 v[64:67], v8 offset:35840
	s_waitcnt lgkmcnt(1)
	v_mul_f32_e32 v179, v41, v73
	v_mul_f32_e32 v69, v59, v73
	v_fmac_f32_e32 v179, v40, v72
	v_fmac_f32_e32 v69, v58, v72
	v_fmac_f32_e32 v179, v34, v74
	v_fmac_f32_e32 v69, v56, v74
	v_fmac_f32_e32 v179, v35, v75
	v_fmac_f32_e32 v69, v57, v75
	s_waitcnt lgkmcnt(0)
	v_mul_f32_e32 v175, v37, v65
	v_mul_f32_e32 v65, v63, v65
	v_fmac_f32_e32 v175, v36, v64
	v_fmac_f32_e32 v65, v62, v64
	v_add_f32_e32 v188, v178, v179
	v_add_f32_e32 v78, v68, v69
	v_fmac_f32_e32 v175, v32, v66
	v_fmac_f32_e32 v65, v60, v66
	ds_read_b128 v[68:71], v8 offset:37888
	ds_read_b128 v[72:75], v8 offset:36864
	v_fmac_f32_e32 v175, v33, v67
	v_fmac_f32_e32 v65, v61, v67
	v_add_f32_e32 v193, v188, v175
	v_add_f32_e32 v83, v78, v65
	ds_read_b128 v[64:67], v8 offset:39936
	ds_read_b128 v[78:81], v8 offset:38912
	s_waitcnt lgkmcnt(3)
	v_mul_f32_e32 v178, v44, v68
	v_mul_f32_e32 v68, v54, v68
	s_waitcnt lgkmcnt(2)
	v_mul_f32_e32 v182, v46, v72
	v_mul_f32_e32 v72, v48, v72
	v_fmac_f32_e32 v182, v47, v73
	v_fmac_f32_e32 v72, v49, v73
	v_fmac_f32_e32 v182, v42, v74
	v_fmac_f32_e32 v72, v50, v74
	v_fmac_f32_e32 v178, v45, v69
	v_fmac_f32_e32 v68, v55, v69
	s_waitcnt lgkmcnt(0)
	v_mul_f32_e32 v179, v40, v78
	v_mul_f32_e32 v69, v58, v78
	v_fmac_f32_e32 v182, v43, v75
	v_fmac_f32_e32 v72, v51, v75
	v_fmac_f32_e32 v178, v38, v70
	v_fmac_f32_e32 v68, v52, v70
	v_fmac_f32_e32 v179, v41, v79
	v_fmac_f32_e32 v69, v59, v79
	v_add_f32_e32 v182, 0, v182
	v_add_f32_e32 v72, 0, v72
	v_fmac_f32_e32 v178, v39, v71
	v_fmac_f32_e32 v68, v53, v71
	v_fmac_f32_e32 v179, v34, v80
	v_fmac_f32_e32 v69, v56, v80
	v_mul_f32_e32 v174, v36, v64
	v_mul_f32_e32 v64, v62, v64
	v_add_f32_e32 v178, v178, v182
	v_add_f32_e32 v68, v68, v72
	v_fmac_f32_e32 v179, v35, v81
	v_fmac_f32_e32 v69, v57, v81
	v_fmac_f32_e32 v174, v37, v65
	v_fmac_f32_e32 v64, v63, v65
	v_add_f32_e32 v188, v179, v178
	v_add_f32_e32 v78, v69, v68
	v_fmac_f32_e32 v174, v32, v66
	v_fmac_f32_e32 v64, v60, v66
	ds_read_b128 v[68:71], v8 offset:41984
	ds_read_b128 v[72:75], v8 offset:40960
	v_fmac_f32_e32 v174, v33, v67
	v_fmac_f32_e32 v64, v61, v67
	v_add_f32_e32 v196, v174, v188
	v_add_f32_e32 v86, v64, v78
	ds_read_b128 v[64:67], v8 offset:44032
	ds_read_b128 v[78:81], v8 offset:43008
	s_waitcnt lgkmcnt(3)
	v_mul_f32_e32 v178, v44, v68
	v_mul_f32_e32 v68, v54, v68
	s_waitcnt lgkmcnt(2)
	v_mul_f32_e32 v182, v46, v72
	v_mul_f32_e32 v72, v48, v72
	v_fmac_f32_e32 v182, v47, v73
	v_fmac_f32_e32 v72, v49, v73
	v_fmac_f32_e32 v182, v42, v74
	v_fmac_f32_e32 v72, v50, v74
	v_fmac_f32_e32 v178, v45, v69
	v_fmac_f32_e32 v68, v55, v69
	s_waitcnt lgkmcnt(0)
	v_mul_f32_e32 v179, v40, v78
	v_mul_f32_e32 v69, v58, v78
	v_fmac_f32_e32 v182, v43, v75
	v_fmac_f32_e32 v72, v51, v75
	v_fmac_f32_e32 v178, v38, v70
	v_fmac_f32_e32 v68, v52, v70
	v_fmac_f32_e32 v179, v41, v79
	v_fmac_f32_e32 v69, v59, v79
	v_add_f32_e32 v182, 0, v182
	v_add_f32_e32 v72, 0, v72
	v_fmac_f32_e32 v178, v39, v71
	v_fmac_f32_e32 v68, v53, v71
	v_fmac_f32_e32 v179, v34, v80
	v_fmac_f32_e32 v69, v56, v80
	v_mul_f32_e32 v174, v36, v64
	v_mul_f32_e32 v64, v62, v64
	v_add_f32_e32 v178, v178, v182
	v_add_f32_e32 v68, v68, v72
	v_fmac_f32_e32 v179, v35, v81
	v_fmac_f32_e32 v69, v57, v81
	v_fmac_f32_e32 v174, v37, v65
	v_fmac_f32_e32 v64, v63, v65
	v_add_f32_e32 v188, v179, v178
	v_add_f32_e32 v78, v69, v68
	v_fmac_f32_e32 v174, v32, v66
	v_fmac_f32_e32 v64, v60, v66
	ds_read_b128 v[68:71], v8 offset:46080
	ds_read_b128 v[72:75], v8 offset:45056
	v_fmac_f32_e32 v174, v33, v67
	v_fmac_f32_e32 v64, v61, v67
	v_add_f32_e32 v197, v174, v188
	v_add_f32_e32 v87, v64, v78
	ds_read_b128 v[64:67], v8 offset:48128
	ds_read_b128 v[78:81], v8 offset:47104
	s_waitcnt lgkmcnt(3)
	v_mul_f32_e32 v178, v44, v68
	v_mul_f32_e32 v68, v54, v68
	s_waitcnt lgkmcnt(2)
	v_mul_f32_e32 v182, v46, v72
	v_mul_f32_e32 v72, v48, v72
	v_fmac_f32_e32 v182, v47, v73
	v_fmac_f32_e32 v72, v49, v73
	v_fmac_f32_e32 v182, v42, v74
	v_fmac_f32_e32 v72, v50, v74
	v_fmac_f32_e32 v178, v45, v69
	v_fmac_f32_e32 v68, v55, v69
	s_waitcnt lgkmcnt(0)
	v_mul_f32_e32 v179, v40, v78
	v_mul_f32_e32 v69, v58, v78
	v_fmac_f32_e32 v182, v43, v75
	v_fmac_f32_e32 v72, v51, v75
	v_fmac_f32_e32 v178, v38, v70
	v_fmac_f32_e32 v68, v52, v70
	v_fmac_f32_e32 v179, v41, v79
	v_fmac_f32_e32 v69, v59, v79
	v_mul_f32_e32 v174, v36, v64
	v_mul_f32_e32 v64, v62, v64
	v_add_f32_e32 v182, 0, v182
	v_add_f32_e32 v72, 0, v72
	v_fmac_f32_e32 v178, v39, v71
	v_fmac_f32_e32 v68, v53, v71
	v_fmac_f32_e32 v179, v34, v80
	v_fmac_f32_e32 v69, v56, v80
	v_fmac_f32_e32 v174, v37, v65
	v_fmac_f32_e32 v64, v63, v65
	v_add_f32_e32 v178, v178, v182
	v_add_f32_e32 v68, v68, v72
	v_fmac_f32_e32 v179, v35, v81
	v_fmac_f32_e32 v69, v57, v81
	v_fmac_f32_e32 v174, v32, v66
	v_fmac_f32_e32 v64, v60, v66
	v_add_f32_e32 v178, v179, v178
	v_add_f32_e32 v68, v69, v68
	v_fmac_f32_e32 v174, v33, v67
	v_fmac_f32_e32 v64, v61, v67
	v_add_f32_e32 v198, v174, v178
	v_add_f32_e32 v88, v64, v68
	ds_read_b128 v[64:67], v8 offset:49152
	ds_read_b128 v[68:71], v8 offset:50176
	ds_read_b128 v[72:75], v8 offset:51200
	s_waitcnt lgkmcnt(2)
; DI void phase7(const Params& p, char* smem) {
;     ...
; #pragma unroll
;     for (int e = 0; e < 16; ++e) {
;       float s = 0.f;
; #pragma unroll
;       for (int i = 0; i < 4; ++i) { const float4 wv = *(const float4*)(wr + e * DM + lane * 4 + 256 * i); s += v[i].x * wv.x + v[i].y * wv.y + v[i].z * wv.z + v[i].w * wv.w; }
;       a[e] = s;
;       if ((e & 3) == 3) __builtin_amdgcn_sched_barrier(0);
;     }
;     float a8[8], a4[4], a2[2], a1;
;     {
;       const bool up = lane & 32;
; #pragma unroll
;       for (int j = 0; j < 8; ++j) { const float send = up ? a[j] : a[j + 8]; const float keep = up ? a[j + 8] : a[j]; a8[j] = keep + __shfl_xor(send, 32); }
	v_mul_f32_e32 v175, v47, v65
	v_mul_f32_e32 v65, v49, v65
	s_waitcnt lgkmcnt(1)
	v_mul_f32_e32 v179, v45, v69
	v_mul_f32_e32 v69, v55, v69
	v_fmac_f32_e32 v175, v46, v64
	v_fmac_f32_e32 v65, v48, v64
	v_fmac_f32_e32 v179, v44, v68
	v_fmac_f32_e32 v69, v54, v68
	v_fmac_f32_e32 v175, v42, v66
	v_fmac_f32_e32 v65, v50, v66
	v_fmac_f32_e32 v175, v43, v67
	v_fmac_f32_e32 v65, v51, v67
	v_fmac_f32_e32 v179, v38, v70
	v_fmac_f32_e32 v69, v52, v70
	v_add_f32_e32 v174, 0, v175
	v_add_f32_e32 v64, 0, v65
	v_fmac_f32_e32 v179, v39, v71
	v_fmac_f32_e32 v69, v53, v71
	v_add_f32_e32 v178, v174, v179
	v_add_f32_e32 v68, v64, v69
	ds_read_b128 v[64:67], v8 offset:52224
	s_waitcnt lgkmcnt(1)
	v_mul_f32_e32 v179, v41, v73
	v_mul_f32_e32 v69, v59, v73
	v_fmac_f32_e32 v179, v40, v72
	v_fmac_f32_e32 v69, v58, v72
	v_fmac_f32_e32 v179, v34, v74
	v_fmac_f32_e32 v69, v56, v74
	v_fmac_f32_e32 v179, v35, v75
	v_fmac_f32_e32 v69, v57, v75
	s_waitcnt lgkmcnt(0)
	v_mul_f32_e32 v175, v37, v65
	v_mul_f32_e32 v65, v63, v65
	v_fmac_f32_e32 v175, v36, v64
	v_fmac_f32_e32 v65, v62, v64
	v_add_f32_e32 v188, v178, v179
	v_add_f32_e32 v78, v68, v69
	v_fmac_f32_e32 v175, v32, v66
	v_fmac_f32_e32 v65, v60, v66
	ds_read_b128 v[68:71], v8 offset:54272
	ds_read_b128 v[72:75], v8 offset:53248
	v_fmac_f32_e32 v175, v33, v67
	v_fmac_f32_e32 v65, v61, v67
	v_add_f32_e32 v199, v188, v175
	v_add_f32_e32 v89, v78, v65
	ds_read_b128 v[64:67], v8 offset:56320
	ds_read_b128 v[78:81], v8 offset:55296
	s_waitcnt lgkmcnt(3)
	v_mul_f32_e32 v178, v44, v68
	v_mul_f32_e32 v68, v54, v68
	s_waitcnt lgkmcnt(2)
	v_mul_f32_e32 v182, v46, v72
	v_mul_f32_e32 v72, v48, v72
	v_fmac_f32_e32 v182, v47, v73
	v_fmac_f32_e32 v72, v49, v73
	v_fmac_f32_e32 v182, v42, v74
	v_fmac_f32_e32 v72, v50, v74
	v_fmac_f32_e32 v178, v45, v69
	v_fmac_f32_e32 v68, v55, v69
	s_waitcnt lgkmcnt(0)
	v_mul_f32_e32 v179, v40, v78
	v_mul_f32_e32 v69, v58, v78
	v_fmac_f32_e32 v182, v43, v75
	v_fmac_f32_e32 v72, v51, v75
	v_fmac_f32_e32 v178, v38, v70
	v_fmac_f32_e32 v68, v52, v70
	v_fmac_f32_e32 v179, v41, v79
	v_fmac_f32_e32 v69, v59, v79
	v_add_f32_e32 v182, 0, v182
	v_add_f32_e32 v72, 0, v72
	v_fmac_f32_e32 v178, v39, v71
	v_fmac_f32_e32 v68, v53, v71
	v_fmac_f32_e32 v179, v34, v80
	v_fmac_f32_e32 v69, v56, v80
	v_mul_f32_e32 v174, v36, v64
	v_mul_f32_e32 v64, v62, v64
	v_add_f32_e32 v178, v178, v182
	v_add_f32_e32 v68, v68, v72
	v_fmac_f32_e32 v179, v35, v81
	v_fmac_f32_e32 v69, v57, v81
	v_fmac_f32_e32 v174, v37, v65
	v_fmac_f32_e32 v64, v63, v65
	v_add_f32_e32 v188, v179, v178
	v_add_f32_e32 v78, v69, v68
	v_fmac_f32_e32 v174, v32, v66
	v_fmac_f32_e32 v64, v60, v66
	ds_read_b128 v[68:71], v8 offset:58368
	ds_read_b128 v[72:75], v8 offset:57344
	v_fmac_f32_e32 v174, v33, v67
	v_fmac_f32_e32 v64, v61, v67
	v_add_f32_e32 v200, v174, v188
	v_add_f32_e32 v90, v64, v78
	ds_read_b128 v[64:67], v8 offset:60416
	ds_read_b128 v[78:81], v8 offset:59392
	s_waitcnt lgkmcnt(3)
	v_mul_f32_e32 v178, v44, v68
	v_mul_f32_e32 v68, v54, v68
	s_waitcnt lgkmcnt(2)
	v_mul_f32_e32 v182, v46, v72
	v_mul_f32_e32 v72, v48, v72
	v_fmac_f32_e32 v182, v47, v73
	v_fmac_f32_e32 v72, v49, v73
	v_fmac_f32_e32 v182, v42, v74
	v_fmac_f32_e32 v72, v50, v74
	v_fmac_f32_e32 v178, v45, v69
	v_fmac_f32_e32 v68, v55, v69
	s_waitcnt lgkmcnt(0)
	v_mul_f32_e32 v179, v40, v78
	v_mul_f32_e32 v69, v58, v78
	v_fmac_f32_e32 v182, v43, v75
	v_fmac_f32_e32 v72, v51, v75
	v_fmac_f32_e32 v178, v38, v70
	v_fmac_f32_e32 v68, v52, v70
	v_fmac_f32_e32 v179, v41, v79
	v_fmac_f32_e32 v69, v59, v79
	v_add_f32_e32 v182, 0, v182
	v_add_f32_e32 v72, 0, v72
	v_fmac_f32_e32 v178, v39, v71
	v_fmac_f32_e32 v68, v53, v71
	v_fmac_f32_e32 v179, v34, v80
	v_fmac_f32_e32 v69, v56, v80
	v_add_f32_e32 v178, v178, v182
	v_add_f32_e32 v68, v68, v72
	v_fmac_f32_e32 v179, v35, v81
	v_fmac_f32_e32 v69, v57, v81
	v_add_f32_e32 v188, v179, v178
	v_add_f32_e32 v78, v69, v68
	ds_read_b128 v[68:71], v8 offset:62464
	ds_read_b128 v[72:75], v8 offset:61440
	v_mul_f32_e32 v174, v36, v64
	v_mul_f32_e32 v64, v62, v64
	v_fmac_f32_e32 v174, v37, v65
	v_fmac_f32_e32 v64, v63, v65
	v_fmac_f32_e32 v174, v32, v66
	v_fmac_f32_e32 v64, v60, v66
	v_fmac_f32_e32 v174, v33, v67
	v_fmac_f32_e32 v64, v61, v67
	v_add_f32_e32 v201, v174, v188
	v_add_f32_e32 v91, v64, v78
	ds_read_b128 v[64:67], v8 offset:64512
	ds_read_b128 v[78:81], v8 offset:63488
	s_waitcnt lgkmcnt(2)
	v_mul_f32_e32 v158, v46, v72
	v_mul_f32_e32 v48, v48, v72
	v_fmac_f32_e32 v158, v47, v73
	v_fmac_f32_e32 v48, v49, v73
	v_mul_f32_e32 v159, v44, v68
	v_mul_f32_e32 v49, v54, v68
	v_fmac_f32_e32 v158, v42, v74
	v_fmac_f32_e32 v48, v50, v74
	v_fmac_f32_e32 v159, v45, v69
	v_fmac_f32_e32 v49, v55, v69
	v_fmac_f32_e32 v158, v43, v75
	v_fmac_f32_e32 v48, v51, v75
	v_fmac_f32_e32 v159, v38, v70
	v_fmac_f32_e32 v49, v52, v70
	v_add_f32_e32 v158, 0, v158
	v_add_f32_e32 v48, 0, v48
	v_fmac_f32_e32 v159, v39, v71
	v_fmac_f32_e32 v49, v53, v71
	v_add_f32_e32 v158, v159, v158
	v_add_f32_e32 v48, v49, v48
	s_waitcnt lgkmcnt(0)
	v_mul_f32_e32 v159, v40, v78
	v_mul_f32_e32 v49, v58, v78
	v_fmac_f32_e32 v159, v41, v79
	v_fmac_f32_e32 v49, v59, v79
	v_fmac_f32_e32 v159, v34, v80
	v_fmac_f32_e32 v49, v56, v80
	v_fmac_f32_e32 v159, v35, v81
	v_fmac_f32_e32 v49, v57, v81
	v_add_f32_e32 v158, v159, v158
	v_add_f32_e32 v48, v49, v48
	v_mul_f32_e32 v159, v36, v64
	v_mul_f32_e32 v49, v62, v64
	v_fmac_f32_e32 v159, v37, v65
	v_fmac_f32_e32 v49, v63, v65
	v_fmac_f32_e32 v159, v32, v66
	v_fmac_f32_e32 v49, v60, v66
	v_fmac_f32_e32 v159, v33, v67
	v_fmac_f32_e32 v49, v61, v67
	v_add_f32_e32 v158, v159, v158
	v_add_f32_e32 v48, v49, v48
	v_cndmask_b32_e64 v159, v110, v193, s[4:5]
	v_cndmask_b32_e64 v49, v0, v83, s[4:5]
	v_cndmask_b32_e64 v161, v112, v197, s[4:5]
	v_cndmask_b32_e64 v51, v2, v87, s[4:5]
	ds_bpermute_b32 v159, v11, v159
	ds_bpermute_b32 v49, v11, v49
	ds_bpermute_b32 v161, v11, v161
	ds_bpermute_b32 v51, v11, v51
	v_cndmask_b32_e64 v110, v193, v110, s[4:5]
	v_cndmask_b32_e64 v0, v83, v0, s[4:5]
	v_cndmask_b32_e64 v160, v111, v196, s[4:5]
	v_cndmask_b32_e64 v50, v1, v86, s[4:5]
	v_cndmask_b32_e64 v112, v197, v112, s[4:5]
	v_cndmask_b32_e64 v2, v87, v2, s[4:5]
	ds_bpermute_b32 v160, v11, v160
	ds_bpermute_b32 v50, v11, v50
	s_waitcnt lgkmcnt(2)
; DI void phase7(const Params& p, char* smem) {
;     ...
;       for (int j = 0; j < 8; ++j) { const float send = up ? a[j] : a[j + 8]; const float keep = up ? a[j + 8] : a[j]; a8[j] = keep + __shfl_xor(send, 32); }
;     }
;     {
;       const bool up = lane & 16;
; #pragma unroll
;       for (int j = 0; j < 4; ++j) { const float send = up ? a8[j] : a8[j + 4]; const float keep = up ? a8[j + 4] : a8[j]; a4[j] = keep + __shfl_xor(send, 16); }
;     }
;     {
;       const bool up = lane & 8;
; #pragma unroll
;       for (int j = 0; j < 2; ++j) { const float send = up ? a4[j] : a4[j + 2]; const float keep = up ? a4[j + 2] : a4[j]; a2[j] = keep + __shfl_xor(send, 8); }
;     }
;     {
;       const bool up = lane & 4;
;       const float send = up ? a2[0] : a2[1]; const float keep = up ? a2[1] : a2[0]; a1 = keep + __shfl_xor(send, 4);
;     }
;     a1 += __shfl_xor(a1, 2);
;     a1 += __shfl_xor(a1, 1);
;     float mx = a1;
; #pragma unroll
;     for (int o = 4; o <= 32; o <<= 1) mx = fmaxf(mx, __shfl_xor(mx, o));
;     const float ex = __expf(a1 - mx);
;     float sm = ex;
; #pragma unroll
;     for (int o = 4; o <= 32; o <<= 1) sm += __shfl_xor(sm, o);
;     if ((lane & 3) == 0) {
	v_add_f32_e32 v110, v110, v159
	v_add_f32_e32 v0, v0, v49
	s_waitcnt lgkmcnt(1)
	v_add_f32_e32 v112, v112, v161
	v_add_f32_e32 v2, v2, v51
	v_cndmask_b32_e64 v159, v113, v198, s[4:5]
	v_cndmask_b32_e64 v49, v3, v88, s[4:5]
	v_cndmask_b32_e64 v161, v119, v200, s[4:5]
	v_cndmask_b32_e64 v51, v9, v90, s[4:5]
	ds_bpermute_b32 v159, v11, v159
	ds_bpermute_b32 v49, v11, v49
	ds_bpermute_b32 v161, v11, v161
	ds_bpermute_b32 v51, v11, v51
	v_cndmask_b32_e64 v111, v196, v111, s[4:5]
	v_cndmask_b32_e64 v1, v86, v1, s[4:5]
	s_waitcnt lgkmcnt(2)
	v_add_f32_e32 v111, v111, v160
	v_add_f32_e32 v1, v1, v50
	v_cndmask_b32_e64 v113, v198, v113, s[4:5]
	v_cndmask_b32_e64 v3, v88, v3, s[4:5]
	v_cndmask_b32_e64 v160, v116, v199, s[4:5]
	v_cndmask_b32_e64 v50, v6, v89, s[4:5]
	v_cndmask_b32_e64 v119, v200, v119, s[4:5]
	v_cndmask_b32_e64 v9, v90, v9, s[4:5]
	ds_bpermute_b32 v160, v11, v160
	ds_bpermute_b32 v50, v11, v50
	s_waitcnt lgkmcnt(2)
	v_add_f32_e32 v113, v113, v159
	v_add_f32_e32 v3, v3, v49
	s_waitcnt lgkmcnt(1)
	v_add_f32_e32 v119, v119, v161
	v_add_f32_e32 v9, v9, v51
	v_cndmask_b32_e64 v159, v186, v201, s[4:5]
	v_cndmask_b32_e64 v49, v76, v91, s[4:5]
	v_cndmask_b32_e64 v161, v192, v158, s[4:5]
	v_cndmask_b32_e64 v51, v82, v48, s[4:5]
	ds_bpermute_b32 v159, v11, v159
	ds_bpermute_b32 v49, v11, v49
	ds_bpermute_b32 v161, v11, v161
	ds_bpermute_b32 v51, v11, v51
	v_cndmask_b32_e64 v116, v199, v116, s[4:5]
	v_cndmask_b32_e64 v6, v89, v6, s[4:5]
	s_waitcnt lgkmcnt(2)
	v_add_f32_e32 v116, v116, v160
	v_add_f32_e32 v6, v6, v50
	v_cndmask_b32_e64 v160, v201, v186, s[4:5]
	v_cndmask_b32_e64 v50, v91, v76, s[4:5]
	v_cndmask_b32_e64 v158, v158, v192, s[4:5]
	v_cndmask_b32_e64 v48, v48, v82, s[4:5]
	s_waitcnt lgkmcnt(1)
	v_add_f32_e32 v159, v160, v159
	v_add_f32_e32 v49, v50, v49
	s_waitcnt lgkmcnt(0)
	v_add_f32_e32 v158, v158, v161
	v_add_f32_e32 v48, v48, v51
	v_cndmask_b32_e64 v162, v110, v116, s[6:7]
	v_cndmask_b32_e64 v52, v0, v6, s[6:7]
	v_cndmask_b32_e64 v110, v116, v110, s[6:7]
	v_cndmask_b32_e64 v0, v6, v0, s[6:7]
	v_cndmask_b32_e64 v116, v111, v119, s[6:7]
	v_cndmask_b32_e64 v6, v1, v9, s[6:7]
	v_cndmask_b32_e64 v111, v119, v111, s[6:7]
	v_cndmask_b32_e64 v1, v9, v1, s[6:7]
	v_cndmask_b32_e64 v119, v112, v159, s[6:7]
	v_cndmask_b32_e64 v9, v2, v49, s[6:7]
	v_cndmask_b32_e64 v160, v113, v158, s[6:7]
	v_cndmask_b32_e64 v50, v3, v48, s[6:7]
	ds_bpermute_b32 v162, v13, v162
	ds_bpermute_b32 v52, v13, v52
	ds_bpermute_b32 v116, v13, v116
	ds_bpermute_b32 v6, v13, v6
	ds_bpermute_b32 v119, v13, v119
	ds_bpermute_b32 v9, v13, v9
	ds_bpermute_b32 v160, v13, v160
	ds_bpermute_b32 v50, v13, v50
	v_cndmask_b32_e64 v112, v159, v112, s[6:7]
	v_cndmask_b32_e64 v2, v49, v2, s[6:7]
	v_cndmask_b32_e64 v113, v158, v113, s[6:7]
	v_cndmask_b32_e64 v3, v48, v3, s[6:7]
	s_waitcnt lgkmcnt(3)
	v_add_f32_e32 v110, v110, v162
	v_add_f32_e32 v0, v0, v52
	s_waitcnt lgkmcnt(2)
	v_add_f32_e32 v111, v111, v116
	v_add_f32_e32 v1, v1, v6
	s_waitcnt lgkmcnt(1)
	v_add_f32_e32 v112, v112, v119
	v_add_f32_e32 v2, v2, v9
	s_waitcnt lgkmcnt(0)
	v_add_f32_e32 v113, v113, v160
	v_add_f32_e32 v3, v3, v50
	v_cndmask_b32_e64 v116, v110, v112, s[8:9]
	v_cndmask_b32_e64 v6, v0, v2, s[8:9]
	v_cndmask_b32_e64 v119, v111, v113, s[8:9]
	v_cndmask_b32_e64 v9, v1, v3, s[8:9]
	ds_bpermute_b32 v116, v15, v116
	ds_bpermute_b32 v6, v15, v6
	ds_bpermute_b32 v119, v15, v119
	ds_bpermute_b32 v9, v15, v9
	v_cndmask_b32_e64 v110, v112, v110, s[8:9]
	v_cndmask_b32_e64 v0, v2, v0, s[8:9]
	v_cndmask_b32_e64 v111, v113, v111, s[8:9]
	v_cndmask_b32_e64 v1, v3, v1, s[8:9]
	s_waitcnt lgkmcnt(1)
	v_add_f32_e32 v110, v110, v116
	v_add_f32_e32 v0, v0, v6
	s_waitcnt lgkmcnt(0)
	v_add_f32_e32 v111, v111, v119
	v_add_f32_e32 v1, v1, v9
	v_cndmask_b32_e64 v112, v110, v111, s[10:11]
	v_cndmask_b32_e64 v2, v0, v1, s[10:11]
	ds_bpermute_b32 v112, v31, v112
	ds_bpermute_b32 v2, v31, v2
	v_cndmask_b32_e64 v110, v111, v110, s[10:11]
	v_cndmask_b32_e64 v0, v1, v0, s[10:11]
	s_waitcnt lgkmcnt(0)
	v_add_f32_e32 v110, v110, v112
	v_add_f32_e32 v0, v0, v2
	ds_bpermute_b32 v111, v77, v110
	ds_bpermute_b32 v1, v77, v0
	s_waitcnt lgkmcnt(0)
	v_add_f32_e32 v110, v110, v111
	v_add_f32_e32 v0, v0, v1
	ds_bpermute_b32 v111, v84, v110
	ds_bpermute_b32 v1, v84, v0
	s_waitcnt lgkmcnt(0)
	v_add_f32_e32 v110, v110, v111
	v_add_f32_e32 v0, v0, v1
	ds_bpermute_b32 v111, v31, v110
	ds_bpermute_b32 v1, v31, v0
	s_waitcnt lgkmcnt(0)
	v_max_f32_e32 v111, v111, v111
	v_max_f32_e32 v1, v1, v1
	v_max_f32_e32 v111, v110, v111
	v_max_f32_e32 v1, v0, v1
	ds_bpermute_b32 v112, v15, v111
	ds_bpermute_b32 v2, v15, v1
	s_waitcnt lgkmcnt(0)
	v_max_f32_e32 v112, v112, v112
	v_max_f32_e32 v2, v2, v2
	v_max_f32_e32 v111, v111, v112
	v_max_f32_e32 v1, v1, v2
	ds_bpermute_b32 v112, v13, v111
	ds_bpermute_b32 v2, v13, v1
	s_waitcnt lgkmcnt(0)
	v_max_f32_e32 v112, v112, v112
	v_max_f32_e32 v2, v2, v2
	v_max_f32_e32 v111, v111, v112
	v_max_f32_e32 v1, v1, v2
	ds_bpermute_b32 v112, v11, v111
	ds_bpermute_b32 v2, v11, v1
	s_waitcnt lgkmcnt(0)
	v_max_f32_e32 v112, v112, v112
	v_max_f32_e32 v2, v2, v2
	v_max_f32_e32 v111, v111, v112
	v_max_f32_e32 v1, v1, v2
	v_sub_f32_e32 v110, v110, v111
	v_sub_f32_e32 v0, v0, v1
	v_mul_f32_e32 v110, 0x3fb8aa3b, v110
	v_mul_f32_e32 v0, 0x3fb8aa3b, v0
	v_exp_f32_e32 v110, v110
	v_exp_f32_e32 v0, v0
	ds_bpermute_b32 v111, v31, v110
	ds_bpermute_b32 v1, v31, v0
	s_waitcnt lgkmcnt(0)
	v_add_f32_e32 v111, v110, v111
	v_add_f32_e32 v1, v0, v1
	ds_bpermute_b32 v112, v15, v111
	ds_bpermute_b32 v2, v15, v1
	s_waitcnt lgkmcnt(0)
	v_add_f32_e32 v111, v111, v112
	v_add_f32_e32 v1, v1, v2
	ds_bpermute_b32 v112, v13, v111
	ds_bpermute_b32 v2, v13, v1
	s_waitcnt lgkmcnt(0)
	v_add_f32_e32 v111, v111, v112
	v_add_f32_e32 v1, v1, v2
	ds_bpermute_b32 v112, v11, v111
	ds_bpermute_b32 v2, v11, v1
	s_and_saveexec_b64 s[16:17], s[12:13]
	s_xor_b64 s[16:17], exec, s[16:17]
	s_cbranch_execz .LBB0_965
; #define SB_ __builtin_amdgcn_sched_barrier(0)
; DI void phase7(const Params& p, char* smem) {
;     ...
;     const float ex = __expf(a1 - mx);
;     float sm = ex;
; #pragma unroll
;     for (int o = 4; o <= 32; o <<= 1) sm += __shfl_xor(sm, o);
;     if ((lane & 3) == 0) {
;       const int e = (lane >> 2) & 15;
;       p.aff[((size_t)((R >> 11) * NE + e)) * SEQ + (R & 2047)] = ex / sm;
;     }
;     ...
;     router(v0, R0);
;     SB_;
;     if (has1) router(v1, R1);
	s_waitcnt lgkmcnt(0)
	v_add_f32_e32 v1, v1, v2
	v_div_scale_f32 v2, s[38:39], v1, v1, v0
	v_rcp_f32_e32 v3, v2
	v_div_scale_f32 v6, vcc, v0, v1, v0
	v_fma_f32 v9, -v2, v3, 1.0
	v_fmac_f32_e32 v3, v9, v3
	v_mul_f32_e32 v9, v6, v3
	v_fma_f32 v48, -v2, v9, v6
	v_fmac_f32_e32 v9, v48, v3
	v_fma_f32 v2, -v2, v9, v6
	v_div_fmas_f32 v2, v2, v3, v9
	v_div_fixup_f32 v2, v2, v1, v0
	v_ashrrev_i32_e32 v0, 7, v4
	v_and_or_b32 v0, v0, -16, v85
	v_ashrrev_i32_e32 v1, 31, v0
	v_and_b32_e32 v3, 0x7ff, v4
	v_lshlrev_b64 v[0:1], 13, v[0:1]
	v_lshl_add_u64 v[0:1], s[20:21], 0, v[0:1]
	v_lshlrev_b32_e32 v6, 2, v3
	v_lshl_add_u64 v[0:1], v[0:1], 0, v[6:7]
	global_store_dword v[0:1], v2, off
	s_and_b64 s[38:39], exec, s[14:15]
	s_cbranch_scc0 .LBB0_965
	v_mov_b32_e32 v0, v110
	v_mov_b32_e32 v1, v111
	v_mov_b32_e32 v2, v112
	s_waitcnt lgkmcnt(0)
	v_add_f32_e32 v1, v1, v2
	v_div_scale_f32 v2, s[38:39], v1, v1, v0
	v_rcp_f32_e32 v3, v2
	v_div_scale_f32 v6, vcc, v0, v1, v0
	v_fma_f32 v9, -v2, v3, 1.0
	v_fmac_f32_e32 v3, v9, v3
	v_mul_f32_e32 v9, v6, v3
	v_fma_f32 v48, -v2, v9, v6
	v_fmac_f32_e32 v9, v48, v3
	v_fma_f32 v2, -v2, v9, v6
	v_div_fmas_f32 v2, v2, v3, v9
	v_div_fixup_f32 v2, v2, v1, v0
	v_ashrrev_i32_e32 v0, 7, v5
	v_and_or_b32 v0, v0, -16, v85
	v_ashrrev_i32_e32 v1, 31, v0
	v_and_b32_e32 v3, 0x7ff, v5
	v_lshlrev_b64 v[0:1], 13, v[0:1]
	v_lshl_add_u64 v[0:1], s[20:21], 0, v[0:1]
	v_lshlrev_b32_e32 v6, 2, v3
	v_lshl_add_u64 v[0:1], v[0:1], 0, v[6:7]
	global_store_dword v[0:1], v2, off
.LBB0_965:
	s_or_b64 exec, exec, s[16:17]
	s_branch .LBB0_954
